# fused final RMSNorm into phase-11 GEMM epilogue via 4-workgroup barrier per row block; phase 12 and its grid barrier removed
# speedup vs baseline: 1.0241x; 1.0241x over previous
_Z4mega6Paramsii:
	s_mov_b32 s16, s2
	s_load_dwordx16 s[36:51], s[0:1], 0x0
	s_load_dwordx8 s[20:27], s[0:1], 0x80
	s_load_dword s2, s[0:1], 0xb0
	s_load_dwordx2 s[90:91], s[0:1], 0xa8
	s_add_u32 s4, s0, 0xa8
	v_and_b32_e32 v194, 0x3ff, v0
	s_addc_u32 s5, s1, 0
	v_cmp_eq_u32_e64 s[14:15], 0, v194
	s_waitcnt lgkmcnt(0)
	v_writelane_b32 v242, s2, 0
	s_cmp_lt_u32 s16, 0x80
	s_cbranch_scc0 .Lf11_zskip
	s_lshl_b32 s2, s16, 7
	s_add_u32 s6, s26, 0x3c08000
	s_addc_u32 s7, s27, 0
	s_add_u32 s6, s6, s2
	s_addc_u32 s7, s7, 0
	v_mov_b32_e32 v1, 0
	s_and_saveexec_b64 s[2:3], s[14:15]
	global_store_dword v1, v1, s[6:7]
	s_or_b64 exec, exec, s[2:3]
.Lf11_zskip:
	s_and_saveexec_b64 s[2:3], s[14:15]
	s_cbranch_execz .LBB0_2
	s_add_i32 s6, 0, 0x20000
	v_mov_b32_e32 v1, 0
	v_mov_b32_e32 v2, s6
	s_add_i32 s6, 0, 0x20004
	ds_write_b32 v2, v1
	v_mov_b32_e32 v2, s6
	ds_write_b32 v2, v1

.Lf11_next:
	s_and_b64 vcc, exec, s[4:5]
	s_mov_b32 s10, s60
	s_mov_b32 s62, s61
	s_mov_b64 s[42:43], s[38:39]
	s_mov_b64 s[40:41], s[0:1]
	s_cbranch_vccnz .LBB0_1218

.LBB0_1169:
	ds_read_b128 v[128:131], v167
	ds_read_b128 v[132:135], v167 offset:1024
	ds_read_b128 v[136:139], v167 offset:2048
	ds_read_b128 v[156:159], v167 offset:3072
	s_add_u32 s6, s40, 0x100
	s_addc_u32 s7, s41, 0
	s_cmp_eq_u32 s65, 40
	s_cselect_b32 s45, s1, s7
	s_cselect_b32 s44, s0, s6
	s_cselect_b32 s43, s39, s64
	s_cselect_b32 s42, s38, s63
	v_lshl_add_u64 v[202:203], s[40:41], 0, v[148:149]
	s_add_i32 m0, s47, 0xc000
	ds_read_b128 v[160:163], v168
	ds_read_b128 v[172:175], v168 offset:1024
	ds_read_b128 v[176:179], v168 offset:2048
	ds_read_b128 v[180:183], v168 offset:3072
	ds_read_b128 v[184:187], v168 offset:4096
	ds_read_b128 v[188:191], v168 offset:5120
	ds_read_b128 v[194:197], v168 offset:6144
	ds_read_b128 v[198:201], v168 offset:7168
	global_load_lds_dwordx4 v[202:203], off
	v_lshl_add_u64 v[202:203], s[40:41], 0, v[150:151]
	s_add_i32 m0, s47, 0xe000
	s_nop 0
	global_load_lds_dwordx4 v[202:203], off
	s_waitcnt lgkmcnt(8)
	s_barrier
	s_waitcnt lgkmcnt(0)
	s_setprio 1
	s_waitcnt lgkmcnt(0)
	v_mfma_f32_16x16x32_bf16 v[124:127], v[128:131], v[160:163], v[124:127]
	v_mfma_f32_16x16x32_bf16 v[120:123], v[136:139], v[160:163], v[120:123]
	v_mfma_f32_16x16x32_bf16 v[108:111], v[128:131], v[176:179], v[108:111]
	v_mfma_f32_16x16x32_bf16 v[104:107], v[136:139], v[176:179], v[104:107]
	v_mfma_f32_16x16x32_bf16 v[92:95], v[128:131], v[184:187], v[92:95]
	v_mfma_f32_16x16x32_bf16 v[88:91], v[136:139], v[184:187], v[88:91]
	v_mfma_f32_16x16x32_bf16 v[76:79], v[128:131], v[194:197], v[76:79]
	v_mfma_f32_16x16x32_bf16 v[72:75], v[136:139], v[194:197], v[72:75]
	v_mfma_f32_16x16x32_bf16 v[124:127], v[132:135], v[172:175], v[124:127]
	v_mfma_f32_16x16x32_bf16 v[120:123], v[156:159], v[172:175], v[120:123]
	v_mfma_f32_16x16x32_bf16 v[108:111], v[132:135], v[180:183], v[108:111]
	v_mfma_f32_16x16x32_bf16 v[104:107], v[156:159], v[180:183], v[104:107]
	v_mfma_f32_16x16x32_bf16 v[92:95], v[132:135], v[188:191], v[92:95]
	v_mfma_f32_16x16x32_bf16 v[88:91], v[156:159], v[188:191], v[88:91]
	v_mfma_f32_16x16x32_bf16 v[76:79], v[132:135], v[198:201], v[76:79]
	v_mfma_f32_16x16x32_bf16 v[72:75], v[156:159], v[198:201], v[72:75]
	s_setprio 0
	s_barrier
	s_add_i32 s28, s57, s46
	v_lshl_add_u64 v[218:219], s[42:43], 0, v[142:143]
	s_mov_b32 m0, s28
	ds_read_b128 v[202:205], v169
	ds_read_b128 v[206:209], v169 offset:1024
	ds_read_b128 v[210:213], v169 offset:2048
	ds_read_b128 v[214:217], v169 offset:3072
	global_load_lds_dwordx4 v[218:219], off
	v_lshl_add_u64 v[220:221], s[42:43], 0, v[146:147]
	s_add_i32 m0, s28, 0x2000
	s_nop 0
	global_load_lds_dwordx4 v[220:221], off
	s_barrier
	s_waitcnt lgkmcnt(0)
	s_setprio 1
	s_waitcnt lgkmcnt(0)
	v_mfma_f32_16x16x32_bf16 v[116:119], v[202:205], v[160:163], v[116:119]
	v_mfma_f32_16x16x32_bf16 v[112:115], v[210:213], v[160:163], v[112:115]
	v_mfma_f32_16x16x32_bf16 v[100:103], v[202:205], v[176:179], v[100:103]
	v_mfma_f32_16x16x32_bf16 v[96:99], v[210:213], v[176:179], v[96:99]
	v_mfma_f32_16x16x32_bf16 v[84:87], v[202:205], v[184:187], v[84:87]
	v_mfma_f32_16x16x32_bf16 v[80:83], v[210:213], v[184:187], v[80:83]
	v_mfma_f32_16x16x32_bf16 v[68:71], v[202:205], v[194:197], v[68:71]
	v_mfma_f32_16x16x32_bf16 v[64:67], v[210:213], v[194:197], v[64:67]
	v_mfma_f32_16x16x32_bf16 v[116:119], v[206:209], v[172:175], v[116:119]
	v_mfma_f32_16x16x32_bf16 v[112:115], v[214:217], v[172:175], v[112:115]
	v_mfma_f32_16x16x32_bf16 v[100:103], v[206:209], v[180:183], v[100:103]
	v_mfma_f32_16x16x32_bf16 v[96:99], v[214:217], v[180:183], v[96:99]
	v_mfma_f32_16x16x32_bf16 v[84:87], v[206:209], v[188:191], v[84:87]
	v_mfma_f32_16x16x32_bf16 v[80:83], v[214:217], v[188:191], v[80:83]
	v_mfma_f32_16x16x32_bf16 v[68:71], v[206:209], v[198:201], v[68:71]
	v_mfma_f32_16x16x32_bf16 v[64:67], v[214:217], v[198:201], v[64:67]
	s_setprio 0
	s_mov_b32 m0, s47
	v_lshl_add_u64 v[222:223], s[44:45], 0, v[140:141]
	s_barrier
	ds_read_b128 v[160:163], v168 offset:16384
	ds_read_b128 v[172:175], v168 offset:17408
	ds_read_b128 v[176:179], v168 offset:18432
	ds_read_b128 v[180:183], v168 offset:19456
	ds_read_b128 v[184:187], v168 offset:20480
	ds_read_b128 v[188:191], v168 offset:21504
	ds_read_b128 v[194:197], v168 offset:22528
	ds_read_b128 v[198:201], v168 offset:23552
	global_load_lds_dwordx4 v[222:223], off
	v_lshl_add_u64 v[224:225], s[44:45], 0, v[144:145]
	s_mov_b32 m0, s48
	s_nop 0
	global_load_lds_dwordx4 v[224:225], off
	s_barrier
	s_waitcnt lgkmcnt(0)
	s_setprio 1
	s_waitcnt lgkmcnt(0)
	v_mfma_f32_16x16x32_bf16 v[60:63], v[128:131], v[160:163], v[60:63]
	v_mfma_f32_16x16x32_bf16 v[56:59], v[136:139], v[160:163], v[56:59]
	v_mfma_f32_16x16x32_bf16 v[44:47], v[128:131], v[176:179], v[44:47]
	v_mfma_f32_16x16x32_bf16 v[40:43], v[136:139], v[176:179], v[40:43]
	v_mfma_f32_16x16x32_bf16 v[28:31], v[128:131], v[184:187], v[28:31]
	v_mfma_f32_16x16x32_bf16 v[24:27], v[136:139], v[184:187], v[24:27]
	v_mfma_f32_16x16x32_bf16 v[12:15], v[128:131], v[194:197], v[12:15]
	v_mfma_f32_16x16x32_bf16 v[8:11], v[136:139], v[194:197], v[8:11]
	v_mfma_f32_16x16x32_bf16 v[60:63], v[132:135], v[172:175], v[60:63]
	v_mfma_f32_16x16x32_bf16 v[56:59], v[156:159], v[172:175], v[56:59]
	v_mfma_f32_16x16x32_bf16 v[44:47], v[132:135], v[180:183], v[44:47]
	v_mfma_f32_16x16x32_bf16 v[40:43], v[156:159], v[180:183], v[40:43]
	v_mfma_f32_16x16x32_bf16 v[28:31], v[132:135], v[188:191], v[28:31]
	v_mfma_f32_16x16x32_bf16 v[24:27], v[156:159], v[188:191], v[24:27]
	v_mfma_f32_16x16x32_bf16 v[12:15], v[132:135], v[198:201], v[12:15]
	v_mfma_f32_16x16x32_bf16 v[8:11], v[156:159], v[198:201], v[8:11]
	s_setprio 0
	s_barrier
	s_add_u32 s40, s42, 0x2c000
	s_addc_u32 s41, s43, 0
	s_add_i32 s28, s58, s46
	v_lshl_add_u64 v[128:129], s[40:41], 0, v[142:143]
	s_mov_b32 m0, s28
	s_nop 0
	global_load_lds_dwordx4 v[128:129], off
	v_lshl_add_u64 v[128:129], s[40:41], 0, v[146:147]
	s_add_i32 m0, s28, 0x2000
	s_nop 0
	global_load_lds_dwordx4 v[128:129], off
	s_waitcnt vmcnt(6)
	s_barrier
	s_setprio 1
	v_mfma_f32_16x16x32_bf16 v[52:55], v[202:205], v[160:163], v[52:55]
	v_mfma_f32_16x16x32_bf16 v[48:51], v[210:213], v[160:163], v[48:51]
	v_mfma_f32_16x16x32_bf16 v[36:39], v[202:205], v[176:179], v[36:39]
	v_mfma_f32_16x16x32_bf16 v[32:35], v[210:213], v[176:179], v[32:35]
	v_mfma_f32_16x16x32_bf16 v[20:23], v[202:205], v[184:187], v[20:23]
	v_mfma_f32_16x16x32_bf16 v[16:19], v[210:213], v[184:187], v[16:19]
	v_mfma_f32_16x16x32_bf16 v[4:7], v[202:205], v[194:197], v[4:7]
	v_mfma_f32_16x16x32_bf16 v[0:3], v[210:213], v[194:197], v[0:3]
	v_mfma_f32_16x16x32_bf16 v[52:55], v[206:209], v[172:175], v[52:55]
	v_mfma_f32_16x16x32_bf16 v[48:51], v[214:217], v[172:175], v[48:51]
	v_mfma_f32_16x16x32_bf16 v[36:39], v[206:209], v[180:183], v[36:39]
	v_mfma_f32_16x16x32_bf16 v[32:35], v[214:217], v[180:183], v[32:35]
	v_mfma_f32_16x16x32_bf16 v[20:23], v[206:209], v[188:191], v[20:23]
	v_mfma_f32_16x16x32_bf16 v[16:19], v[214:217], v[188:191], v[16:19]
	v_mfma_f32_16x16x32_bf16 v[4:7], v[206:209], v[198:201], v[4:7]
	v_mfma_f32_16x16x32_bf16 v[0:3], v[214:217], v[198:201], v[0:3]
	s_setprio 0
	s_add_i32 s28, 0, 0x18000
	v_add_u32_e32 v156, s28, v165
	s_barrier
	ds_read_b128 v[128:131], v156
	ds_read_b128 v[132:135], v156 offset:1024
	ds_read_b128 v[136:139], v156 offset:2048
	ds_read_b128 v[156:159], v156 offset:3072
	s_add_u32 s40, s44, 0xb0000
	s_addc_u32 s41, s45, 0
	s_mov_b32 m0, s49
	v_lshl_add_u64 v[202:203], s[40:41], 0, v[140:141]
	ds_read_b128 v[160:163], v168 offset:32768
	ds_read_b128 v[172:175], v168 offset:33792
	ds_read_b128 v[176:179], v168 offset:34816
	ds_read_b128 v[180:183], v168 offset:35840
	ds_read_b128 v[184:187], v168 offset:36864
	ds_read_b128 v[188:191], v168 offset:37888
	ds_read_b128 v[194:197], v168 offset:38912
	ds_read_b128 v[198:201], v168 offset:39936
	global_load_lds_dwordx4 v[202:203], off
	v_lshl_add_u64 v[202:203], s[40:41], 0, v[144:145]
	s_mov_b32 m0, s50
	s_nop 0
	global_load_lds_dwordx4 v[202:203], off
	s_waitcnt lgkmcnt(8)
	s_barrier
	s_waitcnt lgkmcnt(0)
	s_setprio 1
	s_waitcnt lgkmcnt(0)
	v_mfma_f32_16x16x32_bf16 v[124:127], v[128:131], v[160:163], v[124:127]
	v_mfma_f32_16x16x32_bf16 v[120:123], v[136:139], v[160:163], v[120:123]
	v_mfma_f32_16x16x32_bf16 v[108:111], v[128:131], v[176:179], v[108:111]
	v_mfma_f32_16x16x32_bf16 v[104:107], v[136:139], v[176:179], v[104:107]
	v_mfma_f32_16x16x32_bf16 v[92:95], v[128:131], v[184:187], v[92:95]
	v_mfma_f32_16x16x32_bf16 v[88:91], v[136:139], v[184:187], v[88:91]
	v_mfma_f32_16x16x32_bf16 v[76:79], v[128:131], v[194:197], v[76:79]
	v_mfma_f32_16x16x32_bf16 v[72:75], v[136:139], v[194:197], v[72:75]
	v_mfma_f32_16x16x32_bf16 v[124:127], v[132:135], v[172:175], v[124:127]
	v_mfma_f32_16x16x32_bf16 v[120:123], v[156:159], v[172:175], v[120:123]
	v_mfma_f32_16x16x32_bf16 v[108:111], v[132:135], v[180:183], v[108:111]
	v_mfma_f32_16x16x32_bf16 v[104:107], v[156:159], v[180:183], v[104:107]
	v_mfma_f32_16x16x32_bf16 v[92:95], v[132:135], v[188:191], v[92:95]
	v_mfma_f32_16x16x32_bf16 v[88:91], v[156:159], v[188:191], v[88:91]
	v_mfma_f32_16x16x32_bf16 v[76:79], v[132:135], v[198:201], v[76:79]
	v_mfma_f32_16x16x32_bf16 v[72:75], v[156:159], v[198:201], v[72:75]
	s_setprio 0
	s_barrier
	s_add_i32 s29, 0, 0x1c000
	s_add_i32 s28, s28, s46
	v_add_u32_e32 v171, s29, v165
	v_lshl_add_u64 v[218:219], v[218:219], 0, s[36:37]
	s_mov_b32 m0, s28
	ds_read_b128 v[202:205], v171
	ds_read_b128 v[206:209], v171 offset:1024
	ds_read_b128 v[210:213], v171 offset:2048
	ds_read_b128 v[214:217], v171 offset:3072
	global_load_lds_dwordx4 v[218:219], off
	v_lshl_add_u64 v[218:219], v[220:221], 0, s[36:37]
	s_add_i32 m0, s28, 0x2000
	s_nop 0
	global_load_lds_dwordx4 v[218:219], off
	s_barrier
	s_waitcnt lgkmcnt(0)
	s_setprio 1
	s_waitcnt lgkmcnt(0)
	v_mfma_f32_16x16x32_bf16 v[116:119], v[202:205], v[160:163], v[116:119]
	v_mfma_f32_16x16x32_bf16 v[112:115], v[210:213], v[160:163], v[112:115]
	v_mfma_f32_16x16x32_bf16 v[100:103], v[202:205], v[176:179], v[100:103]
	v_mfma_f32_16x16x32_bf16 v[96:99], v[210:213], v[176:179], v[96:99]
	v_mfma_f32_16x16x32_bf16 v[84:87], v[202:205], v[184:187], v[84:87]
	v_mfma_f32_16x16x32_bf16 v[80:83], v[210:213], v[184:187], v[80:83]
	v_mfma_f32_16x16x32_bf16 v[68:71], v[202:205], v[194:197], v[68:71]
	v_mfma_f32_16x16x32_bf16 v[64:67], v[210:213], v[194:197], v[64:67]
	v_mfma_f32_16x16x32_bf16 v[116:119], v[206:209], v[172:175], v[116:119]
	v_mfma_f32_16x16x32_bf16 v[112:115], v[214:217], v[172:175], v[112:115]
	v_mfma_f32_16x16x32_bf16 v[100:103], v[206:209], v[180:183], v[100:103]
	v_mfma_f32_16x16x32_bf16 v[96:99], v[214:217], v[180:183], v[96:99]
	v_mfma_f32_16x16x32_bf16 v[84:87], v[206:209], v[188:191], v[84:87]
	v_mfma_f32_16x16x32_bf16 v[80:83], v[214:217], v[188:191], v[80:83]
	v_mfma_f32_16x16x32_bf16 v[68:71], v[206:209], v[198:201], v[68:71]
	v_mfma_f32_16x16x32_bf16 v[64:67], v[214:217], v[198:201], v[64:67]
	s_setprio 0
	s_mov_b32 m0, s54
	v_lshl_add_u64 v[218:219], v[222:223], 0, s[36:37]
	s_barrier
	ds_read_b128 v[160:163], v168 offset:49152
	ds_read_b128 v[172:175], v168 offset:50176
	ds_read_b128 v[176:179], v168 offset:51200
	ds_read_b128 v[180:183], v168 offset:52224
	ds_read_b128 v[184:187], v168 offset:53248
	ds_read_b128 v[188:191], v168 offset:54272
	ds_read_b128 v[194:197], v168 offset:55296
	ds_read_b128 v[198:201], v168 offset:56320
	global_load_lds_dwordx4 v[218:219], off
	v_lshl_add_u64 v[218:219], v[224:225], 0, s[36:37]
	s_mov_b32 m0, s55
	s_nop 0
	global_load_lds_dwordx4 v[218:219], off
	s_barrier
	s_waitcnt lgkmcnt(0)
	s_setprio 1
	s_waitcnt lgkmcnt(0)
	v_mfma_f32_16x16x32_bf16 v[60:63], v[128:131], v[160:163], v[60:63]
	v_mfma_f32_16x16x32_bf16 v[56:59], v[136:139], v[160:163], v[56:59]
	v_mfma_f32_16x16x32_bf16 v[44:47], v[128:131], v[176:179], v[44:47]
	v_mfma_f32_16x16x32_bf16 v[40:43], v[136:139], v[176:179], v[40:43]
	v_mfma_f32_16x16x32_bf16 v[28:31], v[128:131], v[184:187], v[28:31]
	v_mfma_f32_16x16x32_bf16 v[24:27], v[136:139], v[184:187], v[24:27]
	v_mfma_f32_16x16x32_bf16 v[12:15], v[128:131], v[194:197], v[12:15]
	v_mfma_f32_16x16x32_bf16 v[8:11], v[136:139], v[194:197], v[8:11]
	v_mfma_f32_16x16x32_bf16 v[60:63], v[132:135], v[172:175], v[60:63]
	v_mfma_f32_16x16x32_bf16 v[56:59], v[156:159], v[172:175], v[56:59]
	v_mfma_f32_16x16x32_bf16 v[44:47], v[132:135], v[180:183], v[44:47]
	v_mfma_f32_16x16x32_bf16 v[40:43], v[156:159], v[180:183], v[40:43]
	v_mfma_f32_16x16x32_bf16 v[28:31], v[132:135], v[188:191], v[28:31]
	v_mfma_f32_16x16x32_bf16 v[24:27], v[156:159], v[188:191], v[24:27]
	v_mfma_f32_16x16x32_bf16 v[12:15], v[132:135], v[198:201], v[12:15]
	v_mfma_f32_16x16x32_bf16 v[8:11], v[156:159], v[198:201], v[8:11]
	s_setprio 0
	s_barrier
	s_add_u32 s40, s42, 0x2c080
	s_addc_u32 s41, s43, 0
	s_add_i32 s28, s29, s46
	v_lshl_add_u64 v[128:129], s[40:41], 0, v[142:143]
	s_mov_b32 m0, s28
	s_nop 0
	global_load_lds_dwordx4 v[128:129], off
	v_lshl_add_u64 v[128:129], s[40:41], 0, v[146:147]
	s_add_i32 m0, s28, 0x2000
	s_nop 0
	global_load_lds_dwordx4 v[128:129], off
	s_waitcnt vmcnt(6)
	s_barrier
	s_setprio 1
	v_mfma_f32_16x16x32_bf16 v[52:55], v[202:205], v[160:163], v[52:55]
	v_mfma_f32_16x16x32_bf16 v[48:51], v[210:213], v[160:163], v[48:51]
	v_mfma_f32_16x16x32_bf16 v[36:39], v[202:205], v[176:179], v[36:39]
	v_mfma_f32_16x16x32_bf16 v[32:35], v[210:213], v[176:179], v[32:35]
	v_mfma_f32_16x16x32_bf16 v[20:23], v[202:205], v[184:187], v[20:23]
	v_mfma_f32_16x16x32_bf16 v[16:19], v[210:213], v[184:187], v[16:19]
	v_mfma_f32_16x16x32_bf16 v[4:7], v[202:205], v[194:197], v[4:7]
	v_mfma_f32_16x16x32_bf16 v[0:3], v[210:213], v[194:197], v[0:3]
	v_mfma_f32_16x16x32_bf16 v[52:55], v[206:209], v[172:175], v[52:55]
	v_mfma_f32_16x16x32_bf16 v[48:51], v[214:217], v[172:175], v[48:51]
	v_mfma_f32_16x16x32_bf16 v[36:39], v[206:209], v[180:183], v[36:39]
	v_mfma_f32_16x16x32_bf16 v[32:35], v[214:217], v[180:183], v[32:35]
	v_mfma_f32_16x16x32_bf16 v[20:23], v[206:209], v[188:191], v[20:23]
	v_mfma_f32_16x16x32_bf16 v[16:19], v[214:217], v[188:191], v[16:19]
	v_mfma_f32_16x16x32_bf16 v[4:7], v[206:209], v[198:201], v[4:7]
	v_mfma_f32_16x16x32_bf16 v[0:3], v[214:217], v[198:201], v[0:3]
	s_setprio 0
	s_add_i32 s65, s65, 2
	s_add_u32 s63, s63, 0x100
	s_addc_u32 s64, s64, 0
	s_cmp_gt_u32 s65, 41
	s_mov_b64 s[40:41], s[6:7]
	s_barrier
	s_cbranch_scc0 .LBB0_1169
	v_lshl_add_u32 v171, s62, 8, v164
	v_lshl_or_b32 v188, s10, 8, v166
	s_mov_b32 s63, 0xffff0000
	v_lshlrev_b32_e32 v128, 11, v171
	v_lshl_add_u32 v128, v188, 1, v128
	v_lshlrev_b32_e32 v129, 12, v171
	v_lshl_add_u32 v129, v188, 2, v129
	v_lshlrev_b32_e32 v132, 2, v188
	s_mov_b64 s[70:71], s[68:69]
	global_load_dwordx4 v[194:197], v128, s[70:71]
	global_load_dwordx4 v[198:201], v128, s[70:71] offset:64
	s_add_u32 s70, s70, 0x8000
	s_addc_u32 s71, s71, 0
	global_load_dwordx4 v[202:205], v128, s[70:71]
	global_load_dwordx4 v[206:209], v128, s[70:71] offset:64
	s_add_u32 s70, s70, 0x8000
	s_addc_u32 s71, s71, 0
	global_load_dwordx4 v[210:213], v128, s[70:71]
	global_load_dwordx4 v[214:217], v128, s[70:71] offset:64
	s_add_u32 s70, s70, 0x8000
	s_addc_u32 s71, s71, 0
	global_load_dwordx4 v[218:221], v128, s[70:71]
	global_load_dwordx4 v[222:225], v128, s[70:71] offset:64
	s_add_u32 s70, s70, 0x28000
	s_addc_u32 s71, s71, 0
	global_load_dwordx4 v[226:229], v128, s[70:71]
	global_load_dwordx4 v[230:233], v128, s[70:71] offset:64
	s_add_u32 s70, s70, 0x8000
	s_addc_u32 s71, s71, 0
	global_load_dwordx4 v[234:237], v128, s[70:71]
	global_load_dwordx4 v[238:241], v128, s[70:71] offset:64
	s_add_u32 s70, s70, 0x8000
	s_addc_u32 s71, s71, 0
	global_load_dwordx4 v[172:175], v128, s[70:71]
	global_load_dwordx4 v[176:179], v128, s[70:71] offset:64
	s_add_u32 s70, s70, 0x8000
	s_addc_u32 s71, s71, 0
	global_load_dwordx4 v[180:183], v128, s[70:71]
	global_load_dwordx4 v[184:187], v128, s[70:71] offset:64
	s_bfe_u32 s42, s17, 0x20006
	s_lshl_b32 s43, s10, 4
	s_lshl_b32 s42, s42, 2
	s_add_i32 s43, s43, s42
	v_lshl_add_u32 v130, v171, 6, s43
	v_and_b32_e32 v131, 48, v170
	v_lshl_add_u32 v131, v171, 6, v131
	v_xor_b32_e32 v134, 16, v170
	v_xor_b32_e32 v135, 32, v170
	v_lshlrev_b32_e32 v134, 2, v134
	v_lshlrev_b32_e32 v135, 2, v135
	v_cmp_gt_u32_e64 s[64:65], 16, v170
	s_add_u32 s74, s8, 0x2000
	s_addc_u32 s75, s9, 0
	s_lshl_b32 s42, s62, 7
	s_add_u32 s78, s26, 0x3c08000
	s_addc_u32 s79, s27, 0
	s_add_u32 s78, s78, s42
	s_addc_u32 s79, s79, 0
	s_waitcnt vmcnt(14)
	v_lshlrev_b32_e32 v136, 16, v194
	v_and_b32_e32 v137, s63, v194
	v_pk_add_f32 v[124:125], v[124:125], v[136:137]
	v_lshlrev_b32_e32 v138, 16, v195
	v_and_b32_e32 v139, s63, v195
	v_pk_add_f32 v[126:127], v[126:127], v[138:139]
	v_lshlrev_b32_e32 v190, 16, v196
	v_and_b32_e32 v191, s63, v196
	v_pk_add_f32 v[120:121], v[120:121], v[190:191]
	v_lshlrev_b32_e32 v136, 16, v197
	v_and_b32_e32 v137, s63, v197
	v_pk_add_f32 v[122:123], v[122:123], v[136:137]
	v_lshlrev_b32_e32 v138, 16, v198
	v_and_b32_e32 v139, s63, v198
	v_pk_add_f32 v[116:117], v[116:117], v[138:139]
	v_lshlrev_b32_e32 v190, 16, v199
	v_and_b32_e32 v191, s63, v199
	v_pk_add_f32 v[118:119], v[118:119], v[190:191]
	v_lshlrev_b32_e32 v136, 16, v200
	v_and_b32_e32 v137, s63, v200
	v_pk_add_f32 v[112:113], v[112:113], v[136:137]
	v_lshlrev_b32_e32 v138, 16, v201
	v_and_b32_e32 v139, s63, v201
	v_pk_add_f32 v[114:115], v[114:115], v[138:139]
	v_mul_f32_e32 v156, v120, v120
	v_mul_f32_e32 v189, v112, v112
	v_fmac_f32_e32 v156, v121, v121
	v_fmac_f32_e32 v189, v113, v113
	v_fmac_f32_e32 v156, v122, v122
	v_fmac_f32_e32 v189, v114, v114
	v_fmac_f32_e32 v156, v123, v123
	v_fmac_f32_e32 v189, v115, v115
	v_fmac_f32_e32 v156, v124, v124
	v_fmac_f32_e32 v189, v116, v116
	v_fmac_f32_e32 v156, v125, v125
	v_fmac_f32_e32 v189, v117, v117
	v_fmac_f32_e32 v156, v126, v126
	v_fmac_f32_e32 v189, v118, v118
	v_fmac_f32_e32 v156, v127, v127
	v_fmac_f32_e32 v189, v119, v119
	v_add_f32_e32 v156, v156, v189
	s_waitcnt vmcnt(12)
	v_lshlrev_b32_e32 v190, 16, v202
	v_and_b32_e32 v191, s63, v202
	v_pk_add_f32 v[108:109], v[108:109], v[190:191]
	v_lshlrev_b32_e32 v136, 16, v203
	v_and_b32_e32 v137, s63, v203
	v_pk_add_f32 v[110:111], v[110:111], v[136:137]
	v_lshlrev_b32_e32 v138, 16, v204
	v_and_b32_e32 v139, s63, v204
	v_pk_add_f32 v[104:105], v[104:105], v[138:139]
	v_lshlrev_b32_e32 v190, 16, v205
	v_and_b32_e32 v191, s63, v205
	v_pk_add_f32 v[106:107], v[106:107], v[190:191]
	v_lshlrev_b32_e32 v136, 16, v206
	v_and_b32_e32 v137, s63, v206
	v_pk_add_f32 v[100:101], v[100:101], v[136:137]
	v_lshlrev_b32_e32 v138, 16, v207
	v_and_b32_e32 v139, s63, v207
	v_pk_add_f32 v[102:103], v[102:103], v[138:139]
	v_lshlrev_b32_e32 v190, 16, v208
	v_and_b32_e32 v191, s63, v208
	v_pk_add_f32 v[96:97], v[96:97], v[190:191]
	v_lshlrev_b32_e32 v136, 16, v209
	v_and_b32_e32 v137, s63, v209
	v_pk_add_f32 v[98:99], v[98:99], v[136:137]
	v_mul_f32_e32 v157, v104, v104
	v_mul_f32_e32 v189, v96, v96
	v_fmac_f32_e32 v157, v105, v105
	v_fmac_f32_e32 v189, v97, v97
	v_fmac_f32_e32 v157, v106, v106
	v_fmac_f32_e32 v189, v98, v98
	v_fmac_f32_e32 v157, v107, v107
	v_fmac_f32_e32 v189, v99, v99
	v_fmac_f32_e32 v157, v108, v108
	v_fmac_f32_e32 v189, v100, v100
	v_fmac_f32_e32 v157, v109, v109
	v_fmac_f32_e32 v189, v101, v101
	v_fmac_f32_e32 v157, v110, v110
	v_fmac_f32_e32 v189, v102, v102
	v_fmac_f32_e32 v157, v111, v111
	v_fmac_f32_e32 v189, v103, v103
	v_add_f32_e32 v157, v157, v189
	s_waitcnt vmcnt(10)
	v_lshlrev_b32_e32 v138, 16, v210
	v_and_b32_e32 v139, s63, v210
	v_pk_add_f32 v[92:93], v[92:93], v[138:139]
	v_lshlrev_b32_e32 v190, 16, v211
	v_and_b32_e32 v191, s63, v211
	v_pk_add_f32 v[94:95], v[94:95], v[190:191]
	v_lshlrev_b32_e32 v136, 16, v212
	v_and_b32_e32 v137, s63, v212
	v_pk_add_f32 v[88:89], v[88:89], v[136:137]
	v_lshlrev_b32_e32 v138, 16, v213
	v_and_b32_e32 v139, s63, v213
	v_pk_add_f32 v[90:91], v[90:91], v[138:139]
	v_lshlrev_b32_e32 v190, 16, v214
	v_and_b32_e32 v191, s63, v214
	v_pk_add_f32 v[84:85], v[84:85], v[190:191]
	v_lshlrev_b32_e32 v136, 16, v215
	v_and_b32_e32 v137, s63, v215
	v_pk_add_f32 v[86:87], v[86:87], v[136:137]
	v_lshlrev_b32_e32 v138, 16, v216
	v_and_b32_e32 v139, s63, v216
	v_pk_add_f32 v[80:81], v[80:81], v[138:139]
	v_lshlrev_b32_e32 v190, 16, v217
	v_and_b32_e32 v191, s63, v217
	v_pk_add_f32 v[82:83], v[82:83], v[190:191]
	v_mul_f32_e32 v158, v88, v88
	v_mul_f32_e32 v189, v80, v80
	v_fmac_f32_e32 v158, v89, v89
	v_fmac_f32_e32 v189, v81, v81
	v_fmac_f32_e32 v158, v90, v90
	v_fmac_f32_e32 v189, v82, v82
	v_fmac_f32_e32 v158, v91, v91
	v_fmac_f32_e32 v189, v83, v83
	v_fmac_f32_e32 v158, v92, v92
	v_fmac_f32_e32 v189, v84, v84
	v_fmac_f32_e32 v158, v93, v93
	v_fmac_f32_e32 v189, v85, v85
	v_fmac_f32_e32 v158, v94, v94
	v_fmac_f32_e32 v189, v86, v86
	v_fmac_f32_e32 v158, v95, v95
	v_fmac_f32_e32 v189, v87, v87
	v_add_f32_e32 v158, v158, v189
	s_waitcnt vmcnt(8)
	v_lshlrev_b32_e32 v136, 16, v218
	v_and_b32_e32 v137, s63, v218
	v_pk_add_f32 v[76:77], v[76:77], v[136:137]
	v_lshlrev_b32_e32 v138, 16, v219
	v_and_b32_e32 v139, s63, v219
	v_pk_add_f32 v[78:79], v[78:79], v[138:139]
	v_lshlrev_b32_e32 v190, 16, v220
	v_and_b32_e32 v191, s63, v220
	v_pk_add_f32 v[72:73], v[72:73], v[190:191]
	v_lshlrev_b32_e32 v136, 16, v221
	v_and_b32_e32 v137, s63, v221
	v_pk_add_f32 v[74:75], v[74:75], v[136:137]
	v_lshlrev_b32_e32 v138, 16, v222
	v_and_b32_e32 v139, s63, v222
	v_pk_add_f32 v[68:69], v[68:69], v[138:139]
	v_lshlrev_b32_e32 v190, 16, v223
	v_and_b32_e32 v191, s63, v223
	v_pk_add_f32 v[70:71], v[70:71], v[190:191]
	v_lshlrev_b32_e32 v136, 16, v224
	v_and_b32_e32 v137, s63, v224
	v_pk_add_f32 v[64:65], v[64:65], v[136:137]
	v_lshlrev_b32_e32 v138, 16, v225
	v_and_b32_e32 v139, s63, v225
	v_pk_add_f32 v[66:67], v[66:67], v[138:139]
	v_mul_f32_e32 v159, v72, v72
	v_mul_f32_e32 v189, v64, v64
	v_fmac_f32_e32 v159, v73, v73
	v_fmac_f32_e32 v189, v65, v65
	v_fmac_f32_e32 v159, v74, v74
	v_fmac_f32_e32 v189, v66, v66
	v_fmac_f32_e32 v159, v75, v75
	v_fmac_f32_e32 v189, v67, v67
	v_fmac_f32_e32 v159, v76, v76
	v_fmac_f32_e32 v189, v68, v68
	v_fmac_f32_e32 v159, v77, v77
	v_fmac_f32_e32 v189, v69, v69
	v_fmac_f32_e32 v159, v78, v78
	v_fmac_f32_e32 v189, v70, v70
	v_fmac_f32_e32 v159, v79, v79
	v_fmac_f32_e32 v189, v71, v71
	v_add_f32_e32 v159, v159, v189
	s_waitcnt vmcnt(6)
	v_lshlrev_b32_e32 v190, 16, v226
	v_and_b32_e32 v191, s63, v226
	v_pk_add_f32 v[60:61], v[60:61], v[190:191]
	v_lshlrev_b32_e32 v136, 16, v227
	v_and_b32_e32 v137, s63, v227
	v_pk_add_f32 v[62:63], v[62:63], v[136:137]
	v_lshlrev_b32_e32 v138, 16, v228
	v_and_b32_e32 v139, s63, v228
	v_pk_add_f32 v[56:57], v[56:57], v[138:139]
	v_lshlrev_b32_e32 v190, 16, v229
	v_and_b32_e32 v191, s63, v229
	v_pk_add_f32 v[58:59], v[58:59], v[190:191]
	v_lshlrev_b32_e32 v136, 16, v230
	v_and_b32_e32 v137, s63, v230
	v_pk_add_f32 v[52:53], v[52:53], v[136:137]
	v_lshlrev_b32_e32 v138, 16, v231
	v_and_b32_e32 v139, s63, v231
	v_pk_add_f32 v[54:55], v[54:55], v[138:139]
	v_lshlrev_b32_e32 v190, 16, v232
	v_and_b32_e32 v191, s63, v232
	v_pk_add_f32 v[48:49], v[48:49], v[190:191]
	v_lshlrev_b32_e32 v136, 16, v233
	v_and_b32_e32 v137, s63, v233
	v_pk_add_f32 v[50:51], v[50:51], v[136:137]
	v_mul_f32_e32 v160, v56, v56
	v_mul_f32_e32 v189, v48, v48
	v_fmac_f32_e32 v160, v57, v57
	v_fmac_f32_e32 v189, v49, v49
	v_fmac_f32_e32 v160, v58, v58
	v_fmac_f32_e32 v189, v50, v50
	v_fmac_f32_e32 v160, v59, v59
	v_fmac_f32_e32 v189, v51, v51
	v_fmac_f32_e32 v160, v60, v60
	v_fmac_f32_e32 v189, v52, v52
	v_fmac_f32_e32 v160, v61, v61
	v_fmac_f32_e32 v189, v53, v53
	v_fmac_f32_e32 v160, v62, v62
	v_fmac_f32_e32 v189, v54, v54
	v_fmac_f32_e32 v160, v63, v63
	v_fmac_f32_e32 v189, v55, v55
	v_add_f32_e32 v160, v160, v189
	s_waitcnt vmcnt(4)
	v_lshlrev_b32_e32 v138, 16, v234
	v_and_b32_e32 v139, s63, v234
	v_pk_add_f32 v[44:45], v[44:45], v[138:139]
	v_lshlrev_b32_e32 v190, 16, v235
	v_and_b32_e32 v191, s63, v235
	v_pk_add_f32 v[46:47], v[46:47], v[190:191]
	v_lshlrev_b32_e32 v136, 16, v236
	v_and_b32_e32 v137, s63, v236
	v_pk_add_f32 v[40:41], v[40:41], v[136:137]
	v_lshlrev_b32_e32 v138, 16, v237
	v_and_b32_e32 v139, s63, v237
	v_pk_add_f32 v[42:43], v[42:43], v[138:139]
	v_lshlrev_b32_e32 v190, 16, v238
	v_and_b32_e32 v191, s63, v238
	v_pk_add_f32 v[36:37], v[36:37], v[190:191]
	v_lshlrev_b32_e32 v136, 16, v239
	v_and_b32_e32 v137, s63, v239
	v_pk_add_f32 v[38:39], v[38:39], v[136:137]
	v_lshlrev_b32_e32 v138, 16, v240
	v_and_b32_e32 v139, s63, v240
	v_pk_add_f32 v[32:33], v[32:33], v[138:139]
	v_lshlrev_b32_e32 v190, 16, v241
	v_and_b32_e32 v191, s63, v241
	v_pk_add_f32 v[34:35], v[34:35], v[190:191]
	v_mul_f32_e32 v161, v40, v40
	v_mul_f32_e32 v189, v32, v32
	v_fmac_f32_e32 v161, v41, v41
	v_fmac_f32_e32 v189, v33, v33
	v_fmac_f32_e32 v161, v42, v42
	v_fmac_f32_e32 v189, v34, v34
	v_fmac_f32_e32 v161, v43, v43
	v_fmac_f32_e32 v189, v35, v35
	v_fmac_f32_e32 v161, v44, v44
	v_fmac_f32_e32 v189, v36, v36
	v_fmac_f32_e32 v161, v45, v45
	v_fmac_f32_e32 v189, v37, v37
	v_fmac_f32_e32 v161, v46, v46
	v_fmac_f32_e32 v189, v38, v38
	v_fmac_f32_e32 v161, v47, v47
	v_fmac_f32_e32 v189, v39, v39
	v_add_f32_e32 v161, v161, v189
	s_waitcnt vmcnt(2)
	v_lshlrev_b32_e32 v136, 16, v172
	v_and_b32_e32 v137, s63, v172
	v_pk_add_f32 v[28:29], v[28:29], v[136:137]
	v_lshlrev_b32_e32 v138, 16, v173
	v_and_b32_e32 v139, s63, v173
	v_pk_add_f32 v[30:31], v[30:31], v[138:139]
	v_lshlrev_b32_e32 v190, 16, v174
	v_and_b32_e32 v191, s63, v174
	v_pk_add_f32 v[24:25], v[24:25], v[190:191]
	v_lshlrev_b32_e32 v136, 16, v175
	v_and_b32_e32 v137, s63, v175
	v_pk_add_f32 v[26:27], v[26:27], v[136:137]
	v_lshlrev_b32_e32 v138, 16, v176
	v_and_b32_e32 v139, s63, v176
	v_pk_add_f32 v[20:21], v[20:21], v[138:139]
	v_lshlrev_b32_e32 v190, 16, v177
	v_and_b32_e32 v191, s63, v177
	v_pk_add_f32 v[22:23], v[22:23], v[190:191]
	v_lshlrev_b32_e32 v136, 16, v178
	v_and_b32_e32 v137, s63, v178
	v_pk_add_f32 v[16:17], v[16:17], v[136:137]
	v_lshlrev_b32_e32 v138, 16, v179
	v_and_b32_e32 v139, s63, v179
	v_pk_add_f32 v[18:19], v[18:19], v[138:139]
	v_mul_f32_e32 v162, v24, v24
	v_mul_f32_e32 v189, v16, v16
	v_fmac_f32_e32 v162, v25, v25
	v_fmac_f32_e32 v189, v17, v17
	v_fmac_f32_e32 v162, v26, v26
	v_fmac_f32_e32 v189, v18, v18
	v_fmac_f32_e32 v162, v27, v27
	v_fmac_f32_e32 v189, v19, v19
	v_fmac_f32_e32 v162, v28, v28
	v_fmac_f32_e32 v189, v20, v20
	v_fmac_f32_e32 v162, v29, v29
	v_fmac_f32_e32 v189, v21, v21
	v_fmac_f32_e32 v162, v30, v30
	v_fmac_f32_e32 v189, v22, v22
	v_fmac_f32_e32 v162, v31, v31
	v_fmac_f32_e32 v189, v23, v23
	v_add_f32_e32 v162, v162, v189
	s_waitcnt vmcnt(0)
	v_lshlrev_b32_e32 v190, 16, v180
	v_and_b32_e32 v191, s63, v180
	v_pk_add_f32 v[12:13], v[12:13], v[190:191]
	v_lshlrev_b32_e32 v136, 16, v181
	v_and_b32_e32 v137, s63, v181
	v_pk_add_f32 v[14:15], v[14:15], v[136:137]
	v_lshlrev_b32_e32 v138, 16, v182
	v_and_b32_e32 v139, s63, v182
	v_pk_add_f32 v[8:9], v[8:9], v[138:139]
	v_lshlrev_b32_e32 v190, 16, v183
	v_and_b32_e32 v191, s63, v183
	v_pk_add_f32 v[10:11], v[10:11], v[190:191]
	v_lshlrev_b32_e32 v136, 16, v184
	v_and_b32_e32 v137, s63, v184
	v_pk_add_f32 v[4:5], v[4:5], v[136:137]
	v_lshlrev_b32_e32 v138, 16, v185
	v_and_b32_e32 v139, s63, v185
	v_pk_add_f32 v[6:7], v[6:7], v[138:139]
	v_lshlrev_b32_e32 v190, 16, v186
	v_and_b32_e32 v191, s63, v186
	v_pk_add_f32 v[0:1], v[0:1], v[190:191]
	v_lshlrev_b32_e32 v136, 16, v187
	v_and_b32_e32 v137, s63, v187
	v_pk_add_f32 v[2:3], v[2:3], v[136:137]
	v_mul_f32_e32 v163, v8, v8
	v_mul_f32_e32 v189, v0, v0
	v_fmac_f32_e32 v163, v9, v9
	v_fmac_f32_e32 v189, v1, v1
	v_fmac_f32_e32 v163, v10, v10
	v_fmac_f32_e32 v189, v2, v2
	v_fmac_f32_e32 v163, v11, v11
	v_fmac_f32_e32 v189, v3, v3
	v_fmac_f32_e32 v163, v12, v12
	v_fmac_f32_e32 v189, v4, v4
	v_fmac_f32_e32 v163, v13, v13
	v_fmac_f32_e32 v189, v5, v5
	v_fmac_f32_e32 v163, v14, v14
	v_fmac_f32_e32 v189, v6, v6
	v_fmac_f32_e32 v163, v15, v15
	v_fmac_f32_e32 v189, v7, v7
	v_add_f32_e32 v163, v163, v189
	ds_bpermute_b32 v136, v134, v156
	ds_bpermute_b32 v137, v134, v157
	ds_bpermute_b32 v138, v134, v158
	ds_bpermute_b32 v139, v134, v159
	ds_bpermute_b32 v188, v134, v160
	ds_bpermute_b32 v189, v134, v161
	ds_bpermute_b32 v190, v134, v162
	ds_bpermute_b32 v191, v134, v163
	s_waitcnt lgkmcnt(0)
	v_add_f32_e32 v156, v156, v136
	v_add_f32_e32 v157, v157, v137
	v_add_f32_e32 v158, v158, v138
	v_add_f32_e32 v159, v159, v139
	v_add_f32_e32 v160, v160, v188
	v_add_f32_e32 v161, v161, v189
	v_add_f32_e32 v162, v162, v190
	v_add_f32_e32 v163, v163, v191
	ds_bpermute_b32 v136, v135, v156
	ds_bpermute_b32 v137, v135, v157
	ds_bpermute_b32 v138, v135, v158
	ds_bpermute_b32 v139, v135, v159
	ds_bpermute_b32 v188, v135, v160
	ds_bpermute_b32 v189, v135, v161
	ds_bpermute_b32 v190, v135, v162
	ds_bpermute_b32 v191, v135, v163
	s_waitcnt lgkmcnt(0)
	v_add_f32_e32 v156, v156, v136
	v_add_f32_e32 v157, v157, v137
	v_add_f32_e32 v158, v158, v138
	v_add_f32_e32 v159, v159, v139
	v_add_f32_e32 v160, v160, v188
	v_add_f32_e32 v161, v161, v189
	v_add_f32_e32 v162, v162, v190
	v_add_f32_e32 v163, v163, v191
	s_and_saveexec_b64 s[66:67], s[64:65]
	global_store_dword v130, v156, s[8:9]
	global_store_dword v130, v157, s[8:9] offset:1024
	global_store_dword v130, v158, s[8:9] offset:2048
	global_store_dword v130, v159, s[8:9] offset:3072
	global_store_dword v130, v160, s[74:75]
	global_store_dword v130, v161, s[74:75] offset:1024
	global_store_dword v130, v162, s[74:75] offset:2048
	global_store_dword v130, v163, s[74:75] offset:3072
	s_or_b64 exec, exec, s[66:67]
	global_load_dwordx4 v[210:213], v132, s[22:23]
	global_load_dwordx4 v[214:217], v132, s[22:23] offset:16
	global_load_dwordx4 v[218:221], v132, s[22:23] offset:128
	global_load_dwordx4 v[222:225], v132, s[22:23] offset:144
	s_waitcnt vmcnt(0)
	s_barrier
	s_barrier
	s_cmpk_gt_u32 s17, 0xff
	s_cbranch_scc1 .Lf11_w1_a
	s_and_saveexec_b64 s[40:41], s[14:15]
	s_cbranch_execz .Lf11_t0_done
	buffer_wbl2 sc1
	s_waitcnt vmcnt(0)
	v_mov_b32_e32 v133, 0
	v_mov_b32_e32 v189, 1
	global_atomic_add v133, v189, s[78:79]
	s_mov_b32 s80, 0
.Lf11_spin:
	global_load_dword v189, v133, s[78:79] sc1
	s_waitcnt vmcnt(0)
	v_cmp_lt_u32_e32 vcc, 3, v189
	s_cbranch_vccnz .Lf11_spin_done
	s_sleep 1
	s_add_i32 s80, s80, 1
	s_cmp_lt_u32 s80, 0x4000
	s_cbranch_scc1 .Lf11_spin
.Lf11_spin_done:
	buffer_inv sc1
	s_waitcnt vmcnt(0)
.Lf11_t0_done:
	s_or_b64 exec, exec, s[40:41]
	s_barrier
.Lf11_w1_a:
	global_load_dwordx4 v[226:229], v131, s[8:9]
	global_load_dwordx4 v[230:233], v131, s[8:9] offset:1024
	global_load_dwordx4 v[234:237], v131, s[8:9] offset:2048
	global_load_dwordx4 v[238:241], v131, s[8:9] offset:3072
	global_load_dwordx4 v[172:175], v131, s[74:75]
	global_load_dwordx4 v[176:179], v131, s[74:75] offset:1024
	global_load_dwordx4 v[180:183], v131, s[74:75] offset:2048
	global_load_dwordx4 v[184:187], v131, s[74:75] offset:3072
	s_mov_b64 s[76:77], s[24:25]
	s_mov_b32 s84, 0x3a800000
	v_mov_b32_e32 v133, 0x358637bd
	s_waitcnt vmcnt(7)
	v_add_f32_e32 v226, v226, v227
	v_add_f32_e32 v228, v228, v229
	v_add_f32_e32 v156, v226, v228
	s_waitcnt vmcnt(6)
	v_add_f32_e32 v230, v230, v231
	v_add_f32_e32 v232, v232, v233
	v_add_f32_e32 v157, v230, v232
	s_waitcnt vmcnt(5)
	v_add_f32_e32 v234, v234, v235
	v_add_f32_e32 v236, v236, v237
	v_add_f32_e32 v158, v234, v236
	s_waitcnt vmcnt(4)
	v_add_f32_e32 v238, v238, v239
	v_add_f32_e32 v240, v240, v241
	v_add_f32_e32 v159, v238, v240
	s_waitcnt vmcnt(3)
	v_add_f32_e32 v172, v172, v173
	v_add_f32_e32 v174, v174, v175
	v_add_f32_e32 v160, v172, v174
	s_waitcnt vmcnt(2)
	v_add_f32_e32 v176, v176, v177
	v_add_f32_e32 v178, v178, v179
	v_add_f32_e32 v161, v176, v178
	s_waitcnt vmcnt(1)
	v_add_f32_e32 v180, v180, v181
	v_add_f32_e32 v182, v182, v183
	v_add_f32_e32 v162, v180, v182
	s_waitcnt vmcnt(0)
	v_add_f32_e32 v184, v184, v185
	v_add_f32_e32 v186, v186, v187
	v_add_f32_e32 v163, v184, v186
	ds_bpermute_b32 v136, v134, v156
	ds_bpermute_b32 v137, v134, v157
	ds_bpermute_b32 v138, v134, v158
	ds_bpermute_b32 v139, v134, v159
	ds_bpermute_b32 v188, v134, v160
	ds_bpermute_b32 v189, v134, v161
	ds_bpermute_b32 v190, v134, v162
	ds_bpermute_b32 v191, v134, v163
	s_waitcnt lgkmcnt(0)
	v_add_f32_e32 v156, v156, v136
	v_add_f32_e32 v157, v157, v137
	v_add_f32_e32 v158, v158, v138
	v_add_f32_e32 v159, v159, v139
	v_add_f32_e32 v160, v160, v188
	v_add_f32_e32 v161, v161, v189
	v_add_f32_e32 v162, v162, v190
	v_add_f32_e32 v163, v163, v191
	ds_bpermute_b32 v136, v135, v156
	ds_bpermute_b32 v137, v135, v157
	ds_bpermute_b32 v138, v135, v158
	ds_bpermute_b32 v139, v135, v159
	ds_bpermute_b32 v188, v135, v160
	ds_bpermute_b32 v189, v135, v161
	ds_bpermute_b32 v190, v135, v162
	ds_bpermute_b32 v191, v135, v163
	s_waitcnt lgkmcnt(0)
	v_add_f32_e32 v156, v156, v136
	v_add_f32_e32 v157, v157, v137
	v_add_f32_e32 v158, v158, v138
	v_add_f32_e32 v159, v159, v139
	v_add_f32_e32 v160, v160, v188
	v_add_f32_e32 v161, v161, v189
	v_add_f32_e32 v162, v162, v190
	v_add_f32_e32 v163, v163, v191
	v_fma_f32 v156, v156, s84, v133
	v_fma_f32 v157, v157, s84, v133
	v_fma_f32 v158, v158, s84, v133
	v_fma_f32 v159, v159, s84, v133
	v_fma_f32 v160, v160, s84, v133
	v_fma_f32 v161, v161, s84, v133
	v_fma_f32 v162, v162, s84, v133
	v_fma_f32 v163, v163, s84, v133
	v_rsq_f32_e32 v194, v156
	v_rsq_f32_e32 v196, v157
	v_rsq_f32_e32 v198, v158
	v_rsq_f32_e32 v200, v159
	v_rsq_f32_e32 v202, v160
	v_rsq_f32_e32 v204, v161
	v_rsq_f32_e32 v206, v162
	v_rsq_f32_e32 v208, v163
	s_nop 0
	v_pk_mul_f32 v[124:125], v[124:125], v[194:195] op_sel_hi:[1,0]
	v_pk_mul_f32 v[126:127], v[126:127], v[194:195] op_sel_hi:[1,0]
	v_pk_mul_f32 v[120:121], v[120:121], v[194:195] op_sel_hi:[1,0]
	v_pk_mul_f32 v[122:123], v[122:123], v[194:195] op_sel_hi:[1,0]
	v_pk_mul_f32 v[116:117], v[116:117], v[194:195] op_sel_hi:[1,0]
	v_pk_mul_f32 v[118:119], v[118:119], v[194:195] op_sel_hi:[1,0]
	v_pk_mul_f32 v[112:113], v[112:113], v[194:195] op_sel_hi:[1,0]
	v_pk_mul_f32 v[114:115], v[114:115], v[194:195] op_sel_hi:[1,0]
	v_pk_mul_f32 v[124:125], v[124:125], v[210:211]
	v_pk_mul_f32 v[126:127], v[126:127], v[212:213]
	v_pk_mul_f32 v[120:121], v[120:121], v[214:215]
	v_pk_mul_f32 v[122:123], v[122:123], v[216:217]
	v_pk_mul_f32 v[116:117], v[116:117], v[218:219]
	v_pk_mul_f32 v[118:119], v[118:119], v[220:221]
	v_pk_mul_f32 v[112:113], v[112:113], v[222:223]
	v_pk_mul_f32 v[114:115], v[114:115], v[224:225]
	global_store_dwordx4 v129, v[124:127], s[76:77]
	global_store_dwordx4 v129, v[120:123], s[76:77] offset:16
	global_store_dwordx4 v129, v[116:119], s[76:77] offset:128
	global_store_dwordx4 v129, v[112:115], s[76:77] offset:144
	s_add_u32 s76, s76, 0x10000
	s_addc_u32 s77, s77, 0
	v_pk_mul_f32 v[108:109], v[108:109], v[196:197] op_sel_hi:[1,0]
	v_pk_mul_f32 v[110:111], v[110:111], v[196:197] op_sel_hi:[1,0]
	v_pk_mul_f32 v[104:105], v[104:105], v[196:197] op_sel_hi:[1,0]
	v_pk_mul_f32 v[106:107], v[106:107], v[196:197] op_sel_hi:[1,0]
	v_pk_mul_f32 v[100:101], v[100:101], v[196:197] op_sel_hi:[1,0]
	v_pk_mul_f32 v[102:103], v[102:103], v[196:197] op_sel_hi:[1,0]
	v_pk_mul_f32 v[96:97], v[96:97], v[196:197] op_sel_hi:[1,0]
	v_pk_mul_f32 v[98:99], v[98:99], v[196:197] op_sel_hi:[1,0]
	v_pk_mul_f32 v[108:109], v[108:109], v[210:211]
	v_pk_mul_f32 v[110:111], v[110:111], v[212:213]
	v_pk_mul_f32 v[104:105], v[104:105], v[214:215]
	v_pk_mul_f32 v[106:107], v[106:107], v[216:217]
	v_pk_mul_f32 v[100:101], v[100:101], v[218:219]
	v_pk_mul_f32 v[102:103], v[102:103], v[220:221]
	v_pk_mul_f32 v[96:97], v[96:97], v[222:223]
	v_pk_mul_f32 v[98:99], v[98:99], v[224:225]
	global_store_dwordx4 v129, v[108:111], s[76:77]
	global_store_dwordx4 v129, v[104:107], s[76:77] offset:16
	global_store_dwordx4 v129, v[100:103], s[76:77] offset:128
	global_store_dwordx4 v129, v[96:99], s[76:77] offset:144
	s_add_u32 s76, s76, 0x10000
	s_addc_u32 s77, s77, 0
	v_pk_mul_f32 v[92:93], v[92:93], v[198:199] op_sel_hi:[1,0]
	v_pk_mul_f32 v[94:95], v[94:95], v[198:199] op_sel_hi:[1,0]
	v_pk_mul_f32 v[88:89], v[88:89], v[198:199] op_sel_hi:[1,0]
	v_pk_mul_f32 v[90:91], v[90:91], v[198:199] op_sel_hi:[1,0]
	v_pk_mul_f32 v[84:85], v[84:85], v[198:199] op_sel_hi:[1,0]
	v_pk_mul_f32 v[86:87], v[86:87], v[198:199] op_sel_hi:[1,0]
	v_pk_mul_f32 v[80:81], v[80:81], v[198:199] op_sel_hi:[1,0]
	v_pk_mul_f32 v[82:83], v[82:83], v[198:199] op_sel_hi:[1,0]
	v_pk_mul_f32 v[92:93], v[92:93], v[210:211]
	v_pk_mul_f32 v[94:95], v[94:95], v[212:213]
	v_pk_mul_f32 v[88:89], v[88:89], v[214:215]
	v_pk_mul_f32 v[90:91], v[90:91], v[216:217]
	v_pk_mul_f32 v[84:85], v[84:85], v[218:219]
	v_pk_mul_f32 v[86:87], v[86:87], v[220:221]
	v_pk_mul_f32 v[80:81], v[80:81], v[222:223]
	v_pk_mul_f32 v[82:83], v[82:83], v[224:225]
	global_store_dwordx4 v129, v[92:95], s[76:77]
	global_store_dwordx4 v129, v[88:91], s[76:77] offset:16
	global_store_dwordx4 v129, v[84:87], s[76:77] offset:128
	global_store_dwordx4 v129, v[80:83], s[76:77] offset:144
	s_add_u32 s76, s76, 0x10000
	s_addc_u32 s77, s77, 0
	v_pk_mul_f32 v[76:77], v[76:77], v[200:201] op_sel_hi:[1,0]
	v_pk_mul_f32 v[78:79], v[78:79], v[200:201] op_sel_hi:[1,0]
	v_pk_mul_f32 v[72:73], v[72:73], v[200:201] op_sel_hi:[1,0]
	v_pk_mul_f32 v[74:75], v[74:75], v[200:201] op_sel_hi:[1,0]
	v_pk_mul_f32 v[68:69], v[68:69], v[200:201] op_sel_hi:[1,0]
	v_pk_mul_f32 v[70:71], v[70:71], v[200:201] op_sel_hi:[1,0]
	v_pk_mul_f32 v[64:65], v[64:65], v[200:201] op_sel_hi:[1,0]
	v_pk_mul_f32 v[66:67], v[66:67], v[200:201] op_sel_hi:[1,0]
	v_pk_mul_f32 v[76:77], v[76:77], v[210:211]
	v_pk_mul_f32 v[78:79], v[78:79], v[212:213]
	v_pk_mul_f32 v[72:73], v[72:73], v[214:215]
	v_pk_mul_f32 v[74:75], v[74:75], v[216:217]
	v_pk_mul_f32 v[68:69], v[68:69], v[218:219]
	v_pk_mul_f32 v[70:71], v[70:71], v[220:221]
	v_pk_mul_f32 v[64:65], v[64:65], v[222:223]
	v_pk_mul_f32 v[66:67], v[66:67], v[224:225]
	global_store_dwordx4 v129, v[76:79], s[76:77]
	global_store_dwordx4 v129, v[72:75], s[76:77] offset:16
	global_store_dwordx4 v129, v[68:71], s[76:77] offset:128
	global_store_dwordx4 v129, v[64:67], s[76:77] offset:144
	s_add_u32 s76, s76, 0x50000
	s_addc_u32 s77, s77, 0
	v_pk_mul_f32 v[60:61], v[60:61], v[202:203] op_sel_hi:[1,0]
	v_pk_mul_f32 v[62:63], v[62:63], v[202:203] op_sel_hi:[1,0]
	v_pk_mul_f32 v[56:57], v[56:57], v[202:203] op_sel_hi:[1,0]
	v_pk_mul_f32 v[58:59], v[58:59], v[202:203] op_sel_hi:[1,0]
	v_pk_mul_f32 v[52:53], v[52:53], v[202:203] op_sel_hi:[1,0]
	v_pk_mul_f32 v[54:55], v[54:55], v[202:203] op_sel_hi:[1,0]
	v_pk_mul_f32 v[48:49], v[48:49], v[202:203] op_sel_hi:[1,0]
	v_pk_mul_f32 v[50:51], v[50:51], v[202:203] op_sel_hi:[1,0]
	v_pk_mul_f32 v[60:61], v[60:61], v[210:211]
	v_pk_mul_f32 v[62:63], v[62:63], v[212:213]
	v_pk_mul_f32 v[56:57], v[56:57], v[214:215]
	v_pk_mul_f32 v[58:59], v[58:59], v[216:217]
	v_pk_mul_f32 v[52:53], v[52:53], v[218:219]
	v_pk_mul_f32 v[54:55], v[54:55], v[220:221]
	v_pk_mul_f32 v[48:49], v[48:49], v[222:223]
	v_pk_mul_f32 v[50:51], v[50:51], v[224:225]
	global_store_dwordx4 v129, v[60:63], s[76:77]
	global_store_dwordx4 v129, v[56:59], s[76:77] offset:16
	global_store_dwordx4 v129, v[52:55], s[76:77] offset:128
	global_store_dwordx4 v129, v[48:51], s[76:77] offset:144
	s_add_u32 s76, s76, 0x10000
	s_addc_u32 s77, s77, 0
	v_pk_mul_f32 v[44:45], v[44:45], v[204:205] op_sel_hi:[1,0]
	v_pk_mul_f32 v[46:47], v[46:47], v[204:205] op_sel_hi:[1,0]
	v_pk_mul_f32 v[40:41], v[40:41], v[204:205] op_sel_hi:[1,0]
	v_pk_mul_f32 v[42:43], v[42:43], v[204:205] op_sel_hi:[1,0]
	v_pk_mul_f32 v[36:37], v[36:37], v[204:205] op_sel_hi:[1,0]
	v_pk_mul_f32 v[38:39], v[38:39], v[204:205] op_sel_hi:[1,0]
	v_pk_mul_f32 v[32:33], v[32:33], v[204:205] op_sel_hi:[1,0]
	v_pk_mul_f32 v[34:35], v[34:35], v[204:205] op_sel_hi:[1,0]
	v_pk_mul_f32 v[44:45], v[44:45], v[210:211]
	v_pk_mul_f32 v[46:47], v[46:47], v[212:213]
	v_pk_mul_f32 v[40:41], v[40:41], v[214:215]
	v_pk_mul_f32 v[42:43], v[42:43], v[216:217]
	v_pk_mul_f32 v[36:37], v[36:37], v[218:219]
	v_pk_mul_f32 v[38:39], v[38:39], v[220:221]
	v_pk_mul_f32 v[32:33], v[32:33], v[222:223]
	v_pk_mul_f32 v[34:35], v[34:35], v[224:225]
	global_store_dwordx4 v129, v[44:47], s[76:77]
	global_store_dwordx4 v129, v[40:43], s[76:77] offset:16
	global_store_dwordx4 v129, v[36:39], s[76:77] offset:128
	global_store_dwordx4 v129, v[32:35], s[76:77] offset:144
	s_add_u32 s76, s76, 0x10000
	s_addc_u32 s77, s77, 0
	v_pk_mul_f32 v[28:29], v[28:29], v[206:207] op_sel_hi:[1,0]
	v_pk_mul_f32 v[30:31], v[30:31], v[206:207] op_sel_hi:[1,0]
	v_pk_mul_f32 v[24:25], v[24:25], v[206:207] op_sel_hi:[1,0]
	v_pk_mul_f32 v[26:27], v[26:27], v[206:207] op_sel_hi:[1,0]
	v_pk_mul_f32 v[20:21], v[20:21], v[206:207] op_sel_hi:[1,0]
	v_pk_mul_f32 v[22:23], v[22:23], v[206:207] op_sel_hi:[1,0]
	v_pk_mul_f32 v[16:17], v[16:17], v[206:207] op_sel_hi:[1,0]
	v_pk_mul_f32 v[18:19], v[18:19], v[206:207] op_sel_hi:[1,0]
	v_pk_mul_f32 v[28:29], v[28:29], v[210:211]
	v_pk_mul_f32 v[30:31], v[30:31], v[212:213]
	v_pk_mul_f32 v[24:25], v[24:25], v[214:215]
	v_pk_mul_f32 v[26:27], v[26:27], v[216:217]
	v_pk_mul_f32 v[20:21], v[20:21], v[218:219]
	v_pk_mul_f32 v[22:23], v[22:23], v[220:221]
	v_pk_mul_f32 v[16:17], v[16:17], v[222:223]
	v_pk_mul_f32 v[18:19], v[18:19], v[224:225]
	global_store_dwordx4 v129, v[28:31], s[76:77]
	global_store_dwordx4 v129, v[24:27], s[76:77] offset:16
	global_store_dwordx4 v129, v[20:23], s[76:77] offset:128
	global_store_dwordx4 v129, v[16:19], s[76:77] offset:144
	s_add_u32 s76, s76, 0x10000
	s_addc_u32 s77, s77, 0
	v_pk_mul_f32 v[12:13], v[12:13], v[208:209] op_sel_hi:[1,0]
	v_pk_mul_f32 v[14:15], v[14:15], v[208:209] op_sel_hi:[1,0]
	v_pk_mul_f32 v[8:9], v[8:9], v[208:209] op_sel_hi:[1,0]
	v_pk_mul_f32 v[10:11], v[10:11], v[208:209] op_sel_hi:[1,0]
	v_pk_mul_f32 v[4:5], v[4:5], v[208:209] op_sel_hi:[1,0]
	v_pk_mul_f32 v[6:7], v[6:7], v[208:209] op_sel_hi:[1,0]
	v_pk_mul_f32 v[0:1], v[0:1], v[208:209] op_sel_hi:[1,0]
	v_pk_mul_f32 v[2:3], v[2:3], v[208:209] op_sel_hi:[1,0]
	v_pk_mul_f32 v[12:13], v[12:13], v[210:211]
	v_pk_mul_f32 v[14:15], v[14:15], v[212:213]
	v_pk_mul_f32 v[8:9], v[8:9], v[214:215]
	v_pk_mul_f32 v[10:11], v[10:11], v[216:217]
	v_pk_mul_f32 v[4:5], v[4:5], v[218:219]
	v_pk_mul_f32 v[6:7], v[6:7], v[220:221]
	v_pk_mul_f32 v[0:1], v[0:1], v[222:223]
	v_pk_mul_f32 v[2:3], v[2:3], v[224:225]
	global_store_dwordx4 v129, v[12:15], s[76:77]
	global_store_dwordx4 v129, v[8:11], s[76:77] offset:16
	global_store_dwordx4 v129, v[4:7], s[76:77] offset:128
	global_store_dwordx4 v129, v[0:3], s[76:77] offset:144
	s_cmpk_gt_u32 s17, 0xff
	s_cbranch_scc0 .Lf11_w0_b
	s_barrier
.Lf11_w0_b:
	s_branch .Lf11_next

.LBB0_1221:
.LBB0_1285:
	s_endpgm
